# scan stepper dot products as single 8-deep chains (2 fewer VALU per step; confirmed with scan phases repeated 4x) on top of the attention load/LDS batching
# speedup vs baseline: 1.0091x; 1.0044x over previous
.Lst_chunk:
	v_add_u32_e32 v132, s75, v140
	v_add_u32_e32 v133, s75, v141
	ds_read_b128 v[40:43], v132 offset:256
	ds_read_b128 v[44:47], v132 offset:272
	ds_read_b128 v[48:51], v132 offset:512
	ds_read_b128 v[52:55], v132 offset:528
	ds_read_b128 v[56:59], v132 offset:768
	ds_read_b128 v[60:63], v132 offset:784
	ds_read_b128 v[64:67], v132 offset:1024
	ds_read_b128 v[68:71], v132 offset:1040
	ds_read_b64 v[72:73], v133 offset:1280
	ds_read_b128 v[74:77], v132 offset:1808
	ds_read_b128 v[78:81], v132 offset:1824
	ds_read_b128 v[82:85], v132 offset:2064
	ds_read_b128 v[86:89], v132 offset:2080
	ds_read_b128 v[90:93], v132 offset:2320
	ds_read_b128 v[94:97], v132 offset:2336
	ds_read_b128 v[98:101], v132 offset:2576
	ds_read_b128 v[102:105], v132 offset:2592
	ds_read_b64 v[106:107], v133 offset:2832
	s_waitcnt lgkmcnt(15)
	v_pk_mul_f32 v[32:33], v[0:1], v[40:41] op_sel_hi:[1,0]
	v_pk_fma_f32 v[32:33], v[2:3], v[40:41], v[32:33] op_sel:[0,1,0]
	v_pk_fma_f32 v[32:33], v[4:5], v[42:43], v[32:33] op_sel_hi:[1,0,1]
	v_pk_fma_f32 v[32:33], v[6:7], v[42:43], v[32:33] op_sel:[0,1,0]
	v_pk_fma_f32 v[32:33], v[8:9], v[44:45], v[32:33] op_sel_hi:[1,0,1]
	v_pk_fma_f32 v[32:33], v[10:11], v[44:45], v[32:33] op_sel:[0,1,0]
	v_pk_fma_f32 v[32:33], v[12:13], v[46:47], v[32:33] op_sel_hi:[1,0,1]
	v_pk_fma_f32 v[32:33], v[14:15], v[46:47], v[32:33] op_sel:[0,1,0]
	s_nop 1
	s_waitcnt lgkmcnt(9)
	v_add_f32_dpp v32, v32, v32 row_half_mirror row_mask:0xf bank_mask:0xf bound_ctrl:1
	v_add_f32_dpp v33, v33, v33 row_half_mirror row_mask:0xf bank_mask:0xf bound_ctrl:1
	v_pk_fma_f32 v[16:17], v[72:73], v[56:57], v[0:1] op_sel_hi:[1,0,1]
	v_add_f32_dpp v32, v32, v32 quad_perm:[1,0,3,2] row_mask:0xf bank_mask:0xf bound_ctrl:1
	v_add_f32_dpp v33, v33, v33 quad_perm:[1,0,3,2] row_mask:0xf bank_mask:0xf bound_ctrl:1
	v_pk_fma_f32 v[18:19], v[72:73], v[56:57], v[2:3] op_sel:[0,1,0]
	v_add_f32_dpp v32, v32, v32 quad_perm:[2,3,0,1] row_mask:0xf bank_mask:0xf bound_ctrl:1
	v_add_f32_dpp v33, v33, v33 quad_perm:[2,3,0,1] row_mask:0xf bank_mask:0xf bound_ctrl:1
	v_pk_fma_f32 v[20:21], v[72:73], v[58:59], v[4:5] op_sel_hi:[1,0,1]
	v_pk_fma_f32 v[22:23], v[72:73], v[58:59], v[6:7] op_sel:[0,1,0]
	v_pk_fma_f32 v[24:25], v[72:73], v[60:61], v[8:9] op_sel_hi:[1,0,1]
	v_pk_fma_f32 v[26:27], v[72:73], v[60:61], v[10:11] op_sel:[0,1,0]
	v_pk_fma_f32 v[28:29], v[72:73], v[62:63], v[12:13] op_sel_hi:[1,0,1]
	v_pk_fma_f32 v[30:31], v[72:73], v[62:63], v[14:15] op_sel:[0,1,0]
	v_pk_fma_f32 v[0:1], v[32:33], v[48:49], v[16:17] op_sel_hi:[1,0,1]
	v_pk_fma_f32 v[2:3], v[32:33], v[48:49], v[18:19] op_sel:[0,1,0]
	v_pk_fma_f32 v[4:5], v[32:33], v[50:51], v[20:21] op_sel_hi:[1,0,1]
	v_pk_fma_f32 v[6:7], v[32:33], v[50:51], v[22:23] op_sel:[0,1,0]
	v_pk_fma_f32 v[8:9], v[32:33], v[52:53], v[24:25] op_sel_hi:[1,0,1]
	v_pk_fma_f32 v[10:11], v[32:33], v[52:53], v[26:27] op_sel:[0,1,0]
	v_pk_fma_f32 v[12:13], v[32:33], v[54:55], v[28:29] op_sel_hi:[1,0,1]
	v_pk_fma_f32 v[14:15], v[32:33], v[54:55], v[30:31] op_sel:[0,1,0]
	s_waitcnt lgkmcnt(7)
	v_pk_mul_f32 v[32:33], v[0:1], v[74:75] op_sel_hi:[1,0]
	v_pk_mul_f32 v[36:37], v[0:1], v[64:65] op_sel_hi:[1,0]
	v_pk_fma_f32 v[32:33], v[2:3], v[74:75], v[32:33] op_sel:[0,1,0]
	v_pk_fma_f32 v[36:37], v[2:3], v[64:65], v[36:37] op_sel:[0,1,0]
	v_pk_fma_f32 v[32:33], v[4:5], v[76:77], v[32:33] op_sel_hi:[1,0,1]
	v_pk_fma_f32 v[36:37], v[4:5], v[66:67], v[36:37] op_sel_hi:[1,0,1]
	v_pk_fma_f32 v[32:33], v[6:7], v[76:77], v[32:33] op_sel:[0,1,0]
	v_pk_fma_f32 v[36:37], v[6:7], v[66:67], v[36:37] op_sel:[0,1,0]
	v_pk_fma_f32 v[32:33], v[8:9], v[78:79], v[32:33] op_sel_hi:[1,0,1]
	v_pk_fma_f32 v[36:37], v[8:9], v[68:69], v[36:37] op_sel_hi:[1,0,1]
	v_pk_fma_f32 v[32:33], v[10:11], v[78:79], v[32:33] op_sel:[0,1,0]
	v_pk_fma_f32 v[36:37], v[10:11], v[68:69], v[36:37] op_sel:[0,1,0]
	v_pk_fma_f32 v[32:33], v[12:13], v[80:81], v[32:33] op_sel_hi:[1,0,1]
	v_pk_fma_f32 v[36:37], v[12:13], v[70:71], v[36:37] op_sel_hi:[1,0,1]
	v_pk_fma_f32 v[32:33], v[14:15], v[80:81], v[32:33] op_sel:[0,1,0]
	v_pk_fma_f32 v[36:37], v[14:15], v[70:71], v[36:37] op_sel:[0,1,0]
	ds_write2st64_b32 v134, v36, v37 offset0:0 offset1:1
	ds_read_b128 v[40:43], v132 offset:3360
	ds_read_b128 v[44:47], v132 offset:3376
	ds_read_b128 v[48:51], v132 offset:3616
	ds_read_b128 v[52:55], v132 offset:3632
	ds_read_b128 v[56:59], v132 offset:3872
	ds_read_b128 v[60:63], v132 offset:3888
	ds_read_b128 v[64:67], v132 offset:4128
	ds_read_b128 v[68:71], v132 offset:4144
	ds_read_b64 v[72:73], v133 offset:4384
	s_waitcnt lgkmcnt(10)
	v_add_f32_dpp v32, v32, v32 row_half_mirror row_mask:0xf bank_mask:0xf bound_ctrl:1
	v_add_f32_dpp v33, v33, v33 row_half_mirror row_mask:0xf bank_mask:0xf bound_ctrl:1
	v_pk_fma_f32 v[16:17], v[106:107], v[90:91], v[0:1] op_sel_hi:[1,0,1]
	v_add_f32_dpp v32, v32, v32 quad_perm:[1,0,3,2] row_mask:0xf bank_mask:0xf bound_ctrl:1
	v_add_f32_dpp v33, v33, v33 quad_perm:[1,0,3,2] row_mask:0xf bank_mask:0xf bound_ctrl:1
	v_pk_fma_f32 v[18:19], v[106:107], v[90:91], v[2:3] op_sel:[0,1,0]
	v_add_f32_dpp v32, v32, v32 quad_perm:[2,3,0,1] row_mask:0xf bank_mask:0xf bound_ctrl:1
	v_add_f32_dpp v33, v33, v33 quad_perm:[2,3,0,1] row_mask:0xf bank_mask:0xf bound_ctrl:1
	v_pk_fma_f32 v[20:21], v[106:107], v[92:93], v[4:5] op_sel_hi:[1,0,1]
	v_pk_fma_f32 v[22:23], v[106:107], v[92:93], v[6:7] op_sel:[0,1,0]
	v_pk_fma_f32 v[24:25], v[106:107], v[94:95], v[8:9] op_sel_hi:[1,0,1]
	v_pk_fma_f32 v[26:27], v[106:107], v[94:95], v[10:11] op_sel:[0,1,0]
	v_pk_fma_f32 v[28:29], v[106:107], v[96:97], v[12:13] op_sel_hi:[1,0,1]
	v_pk_fma_f32 v[30:31], v[106:107], v[96:97], v[14:15] op_sel:[0,1,0]
	v_pk_fma_f32 v[0:1], v[32:33], v[82:83], v[16:17] op_sel_hi:[1,0,1]
	v_pk_fma_f32 v[2:3], v[32:33], v[82:83], v[18:19] op_sel:[0,1,0]
	v_pk_fma_f32 v[4:5], v[32:33], v[84:85], v[20:21] op_sel_hi:[1,0,1]
	v_pk_fma_f32 v[6:7], v[32:33], v[84:85], v[22:23] op_sel:[0,1,0]
	v_pk_fma_f32 v[8:9], v[32:33], v[86:87], v[24:25] op_sel_hi:[1,0,1]
	v_pk_fma_f32 v[10:11], v[32:33], v[86:87], v[26:27] op_sel:[0,1,0]
	v_pk_fma_f32 v[12:13], v[32:33], v[88:89], v[28:29] op_sel_hi:[1,0,1]
	v_pk_fma_f32 v[14:15], v[32:33], v[88:89], v[30:31] op_sel:[0,1,0]
	s_waitcnt lgkmcnt(7)
	v_pk_mul_f32 v[32:33], v[0:1], v[40:41] op_sel_hi:[1,0]
	v_pk_mul_f32 v[36:37], v[0:1], v[98:99] op_sel_hi:[1,0]
	v_pk_fma_f32 v[32:33], v[2:3], v[40:41], v[32:33] op_sel:[0,1,0]
	v_pk_fma_f32 v[36:37], v[2:3], v[98:99], v[36:37] op_sel:[0,1,0]
	v_pk_fma_f32 v[32:33], v[4:5], v[42:43], v[32:33] op_sel_hi:[1,0,1]
	v_pk_fma_f32 v[36:37], v[4:5], v[100:101], v[36:37] op_sel_hi:[1,0,1]
	v_pk_fma_f32 v[32:33], v[6:7], v[42:43], v[32:33] op_sel:[0,1,0]
	v_pk_fma_f32 v[36:37], v[6:7], v[100:101], v[36:37] op_sel:[0,1,0]
	v_pk_fma_f32 v[32:33], v[8:9], v[44:45], v[32:33] op_sel_hi:[1,0,1]
	v_pk_fma_f32 v[36:37], v[8:9], v[102:103], v[36:37] op_sel_hi:[1,0,1]
	v_pk_fma_f32 v[32:33], v[10:11], v[44:45], v[32:33] op_sel:[0,1,0]
	v_pk_fma_f32 v[36:37], v[10:11], v[102:103], v[36:37] op_sel:[0,1,0]
	v_pk_fma_f32 v[32:33], v[12:13], v[46:47], v[32:33] op_sel_hi:[1,0,1]
	v_pk_fma_f32 v[36:37], v[12:13], v[104:105], v[36:37] op_sel_hi:[1,0,1]
	v_pk_fma_f32 v[32:33], v[14:15], v[46:47], v[32:33] op_sel:[0,1,0]
	v_pk_fma_f32 v[36:37], v[14:15], v[104:105], v[36:37] op_sel:[0,1,0]
	ds_write2st64_b32 v134, v36, v37 offset0:2 offset1:3
	ds_read_b128 v[74:77], v132 offset:4912
	ds_read_b128 v[78:81], v132 offset:4928
	ds_read_b128 v[82:85], v132 offset:5168
	ds_read_b128 v[86:89], v132 offset:5184
	ds_read_b128 v[90:93], v132 offset:5424
	ds_read_b128 v[94:97], v132 offset:5440
	ds_read_b128 v[98:101], v132 offset:5680
	ds_read_b128 v[102:105], v132 offset:5696
	ds_read_b64 v[106:107], v133 offset:5936
	s_waitcnt lgkmcnt(10)
	v_add_f32_dpp v32, v32, v32 row_half_mirror row_mask:0xf bank_mask:0xf bound_ctrl:1
	v_add_f32_dpp v33, v33, v33 row_half_mirror row_mask:0xf bank_mask:0xf bound_ctrl:1
	v_pk_fma_f32 v[16:17], v[72:73], v[56:57], v[0:1] op_sel_hi:[1,0,1]
	v_add_f32_dpp v32, v32, v32 quad_perm:[1,0,3,2] row_mask:0xf bank_mask:0xf bound_ctrl:1
	v_add_f32_dpp v33, v33, v33 quad_perm:[1,0,3,2] row_mask:0xf bank_mask:0xf bound_ctrl:1
	v_pk_fma_f32 v[18:19], v[72:73], v[56:57], v[2:3] op_sel:[0,1,0]
	v_add_f32_dpp v32, v32, v32 quad_perm:[2,3,0,1] row_mask:0xf bank_mask:0xf bound_ctrl:1
	v_add_f32_dpp v33, v33, v33 quad_perm:[2,3,0,1] row_mask:0xf bank_mask:0xf bound_ctrl:1
	v_pk_fma_f32 v[20:21], v[72:73], v[58:59], v[4:5] op_sel_hi:[1,0,1]
	v_pk_fma_f32 v[22:23], v[72:73], v[58:59], v[6:7] op_sel:[0,1,0]
	v_pk_fma_f32 v[24:25], v[72:73], v[60:61], v[8:9] op_sel_hi:[1,0,1]
	v_pk_fma_f32 v[26:27], v[72:73], v[60:61], v[10:11] op_sel:[0,1,0]
	v_pk_fma_f32 v[28:29], v[72:73], v[62:63], v[12:13] op_sel_hi:[1,0,1]
	v_pk_fma_f32 v[30:31], v[72:73], v[62:63], v[14:15] op_sel:[0,1,0]
	v_pk_fma_f32 v[0:1], v[32:33], v[48:49], v[16:17] op_sel_hi:[1,0,1]
	v_pk_fma_f32 v[2:3], v[32:33], v[48:49], v[18:19] op_sel:[0,1,0]
	v_pk_fma_f32 v[4:5], v[32:33], v[50:51], v[20:21] op_sel_hi:[1,0,1]
	v_pk_fma_f32 v[6:7], v[32:33], v[50:51], v[22:23] op_sel:[0,1,0]
	v_pk_fma_f32 v[8:9], v[32:33], v[52:53], v[24:25] op_sel_hi:[1,0,1]
	v_pk_fma_f32 v[10:11], v[32:33], v[52:53], v[26:27] op_sel:[0,1,0]
	v_pk_fma_f32 v[12:13], v[32:33], v[54:55], v[28:29] op_sel_hi:[1,0,1]
	v_pk_fma_f32 v[14:15], v[32:33], v[54:55], v[30:31] op_sel:[0,1,0]
	s_waitcnt lgkmcnt(7)
	v_pk_mul_f32 v[32:33], v[0:1], v[74:75] op_sel_hi:[1,0]
	v_pk_mul_f32 v[36:37], v[0:1], v[64:65] op_sel_hi:[1,0]
	v_pk_fma_f32 v[32:33], v[2:3], v[74:75], v[32:33] op_sel:[0,1,0]
	v_pk_fma_f32 v[36:37], v[2:3], v[64:65], v[36:37] op_sel:[0,1,0]
	v_pk_fma_f32 v[32:33], v[4:5], v[76:77], v[32:33] op_sel_hi:[1,0,1]
	v_pk_fma_f32 v[36:37], v[4:5], v[66:67], v[36:37] op_sel_hi:[1,0,1]
	v_pk_fma_f32 v[32:33], v[6:7], v[76:77], v[32:33] op_sel:[0,1,0]
	v_pk_fma_f32 v[36:37], v[6:7], v[66:67], v[36:37] op_sel:[0,1,0]
	v_pk_fma_f32 v[32:33], v[8:9], v[78:79], v[32:33] op_sel_hi:[1,0,1]
	v_pk_fma_f32 v[36:37], v[8:9], v[68:69], v[36:37] op_sel_hi:[1,0,1]
	v_pk_fma_f32 v[32:33], v[10:11], v[78:79], v[32:33] op_sel:[0,1,0]
	v_pk_fma_f32 v[36:37], v[10:11], v[68:69], v[36:37] op_sel:[0,1,0]
	v_pk_fma_f32 v[32:33], v[12:13], v[80:81], v[32:33] op_sel_hi:[1,0,1]
	v_pk_fma_f32 v[36:37], v[12:13], v[70:71], v[36:37] op_sel_hi:[1,0,1]
	v_pk_fma_f32 v[32:33], v[14:15], v[80:81], v[32:33] op_sel:[0,1,0]
	v_pk_fma_f32 v[36:37], v[14:15], v[70:71], v[36:37] op_sel:[0,1,0]
	ds_write2st64_b32 v134, v36, v37 offset0:4 offset1:5
	ds_read_b128 v[40:43], v132 offset:6464
	ds_read_b128 v[44:47], v132 offset:6480
	ds_read_b128 v[48:51], v132 offset:6720
	ds_read_b128 v[52:55], v132 offset:6736
	ds_read_b128 v[56:59], v132 offset:6976
	ds_read_b128 v[60:63], v132 offset:6992
	ds_read_b128 v[64:67], v132 offset:7232
	ds_read_b128 v[68:71], v132 offset:7248
	ds_read_b64 v[72:73], v133 offset:7488
	s_waitcnt lgkmcnt(10)
	v_add_f32_dpp v32, v32, v32 row_half_mirror row_mask:0xf bank_mask:0xf bound_ctrl:1
	v_add_f32_dpp v33, v33, v33 row_half_mirror row_mask:0xf bank_mask:0xf bound_ctrl:1
	v_pk_fma_f32 v[16:17], v[106:107], v[90:91], v[0:1] op_sel_hi:[1,0,1]
	v_add_f32_dpp v32, v32, v32 quad_perm:[1,0,3,2] row_mask:0xf bank_mask:0xf bound_ctrl:1
	v_add_f32_dpp v33, v33, v33 quad_perm:[1,0,3,2] row_mask:0xf bank_mask:0xf bound_ctrl:1
	v_pk_fma_f32 v[18:19], v[106:107], v[90:91], v[2:3] op_sel:[0,1,0]
	v_add_f32_dpp v32, v32, v32 quad_perm:[2,3,0,1] row_mask:0xf bank_mask:0xf bound_ctrl:1
	v_add_f32_dpp v33, v33, v33 quad_perm:[2,3,0,1] row_mask:0xf bank_mask:0xf bound_ctrl:1
	v_pk_fma_f32 v[20:21], v[106:107], v[92:93], v[4:5] op_sel_hi:[1,0,1]
	v_pk_fma_f32 v[22:23], v[106:107], v[92:93], v[6:7] op_sel:[0,1,0]
	v_pk_fma_f32 v[24:25], v[106:107], v[94:95], v[8:9] op_sel_hi:[1,0,1]
	v_pk_fma_f32 v[26:27], v[106:107], v[94:95], v[10:11] op_sel:[0,1,0]
	v_pk_fma_f32 v[28:29], v[106:107], v[96:97], v[12:13] op_sel_hi:[1,0,1]
	v_pk_fma_f32 v[30:31], v[106:107], v[96:97], v[14:15] op_sel:[0,1,0]
	v_pk_fma_f32 v[0:1], v[32:33], v[82:83], v[16:17] op_sel_hi:[1,0,1]
	v_pk_fma_f32 v[2:3], v[32:33], v[82:83], v[18:19] op_sel:[0,1,0]
	v_pk_fma_f32 v[4:5], v[32:33], v[84:85], v[20:21] op_sel_hi:[1,0,1]
	v_pk_fma_f32 v[6:7], v[32:33], v[84:85], v[22:23] op_sel:[0,1,0]
	v_pk_fma_f32 v[8:9], v[32:33], v[86:87], v[24:25] op_sel_hi:[1,0,1]
	v_pk_fma_f32 v[10:11], v[32:33], v[86:87], v[26:27] op_sel:[0,1,0]
	v_pk_fma_f32 v[12:13], v[32:33], v[88:89], v[28:29] op_sel_hi:[1,0,1]
	v_pk_fma_f32 v[14:15], v[32:33], v[88:89], v[30:31] op_sel:[0,1,0]
	s_waitcnt lgkmcnt(7)
	v_pk_mul_f32 v[32:33], v[0:1], v[40:41] op_sel_hi:[1,0]
	v_pk_mul_f32 v[36:37], v[0:1], v[98:99] op_sel_hi:[1,0]
	v_pk_fma_f32 v[32:33], v[2:3], v[40:41], v[32:33] op_sel:[0,1,0]
	v_pk_fma_f32 v[36:37], v[2:3], v[98:99], v[36:37] op_sel:[0,1,0]
	v_pk_fma_f32 v[32:33], v[4:5], v[42:43], v[32:33] op_sel_hi:[1,0,1]
	v_pk_fma_f32 v[36:37], v[4:5], v[100:101], v[36:37] op_sel_hi:[1,0,1]
	v_pk_fma_f32 v[32:33], v[6:7], v[42:43], v[32:33] op_sel:[0,1,0]
	v_pk_fma_f32 v[36:37], v[6:7], v[100:101], v[36:37] op_sel:[0,1,0]
	v_pk_fma_f32 v[32:33], v[8:9], v[44:45], v[32:33] op_sel_hi:[1,0,1]
	v_pk_fma_f32 v[36:37], v[8:9], v[102:103], v[36:37] op_sel_hi:[1,0,1]
	v_pk_fma_f32 v[32:33], v[10:11], v[44:45], v[32:33] op_sel:[0,1,0]
	v_pk_fma_f32 v[36:37], v[10:11], v[102:103], v[36:37] op_sel:[0,1,0]
	v_pk_fma_f32 v[32:33], v[12:13], v[46:47], v[32:33] op_sel_hi:[1,0,1]
	v_pk_fma_f32 v[36:37], v[12:13], v[104:105], v[36:37] op_sel_hi:[1,0,1]
	v_pk_fma_f32 v[32:33], v[14:15], v[46:47], v[32:33] op_sel:[0,1,0]
	v_pk_fma_f32 v[36:37], v[14:15], v[104:105], v[36:37] op_sel:[0,1,0]
	ds_write2st64_b32 v134, v36, v37 offset0:6 offset1:7
	ds_read_b128 v[74:77], v132 offset:8016
	ds_read_b128 v[78:81], v132 offset:8032
	ds_read_b128 v[82:85], v132 offset:8272
	ds_read_b128 v[86:89], v132 offset:8288
	ds_read_b128 v[90:93], v132 offset:8528
	ds_read_b128 v[94:97], v132 offset:8544
	ds_read_b128 v[98:101], v132 offset:8784
	ds_read_b128 v[102:105], v132 offset:8800
	ds_read_b64 v[106:107], v133 offset:9040
	s_waitcnt lgkmcnt(10)
	v_add_f32_dpp v32, v32, v32 row_half_mirror row_mask:0xf bank_mask:0xf bound_ctrl:1
	v_add_f32_dpp v33, v33, v33 row_half_mirror row_mask:0xf bank_mask:0xf bound_ctrl:1
	v_pk_fma_f32 v[16:17], v[72:73], v[56:57], v[0:1] op_sel_hi:[1,0,1]
	v_add_f32_dpp v32, v32, v32 quad_perm:[1,0,3,2] row_mask:0xf bank_mask:0xf bound_ctrl:1
	v_add_f32_dpp v33, v33, v33 quad_perm:[1,0,3,2] row_mask:0xf bank_mask:0xf bound_ctrl:1
	v_pk_fma_f32 v[18:19], v[72:73], v[56:57], v[2:3] op_sel:[0,1,0]
	v_add_f32_dpp v32, v32, v32 quad_perm:[2,3,0,1] row_mask:0xf bank_mask:0xf bound_ctrl:1
	v_add_f32_dpp v33, v33, v33 quad_perm:[2,3,0,1] row_mask:0xf bank_mask:0xf bound_ctrl:1
	v_pk_fma_f32 v[20:21], v[72:73], v[58:59], v[4:5] op_sel_hi:[1,0,1]
	v_pk_fma_f32 v[22:23], v[72:73], v[58:59], v[6:7] op_sel:[0,1,0]
	v_pk_fma_f32 v[24:25], v[72:73], v[60:61], v[8:9] op_sel_hi:[1,0,1]
	v_pk_fma_f32 v[26:27], v[72:73], v[60:61], v[10:11] op_sel:[0,1,0]
	v_pk_fma_f32 v[28:29], v[72:73], v[62:63], v[12:13] op_sel_hi:[1,0,1]
	v_pk_fma_f32 v[30:31], v[72:73], v[62:63], v[14:15] op_sel:[0,1,0]
	v_pk_fma_f32 v[0:1], v[32:33], v[48:49], v[16:17] op_sel_hi:[1,0,1]
	v_pk_fma_f32 v[2:3], v[32:33], v[48:49], v[18:19] op_sel:[0,1,0]
	v_pk_fma_f32 v[4:5], v[32:33], v[50:51], v[20:21] op_sel_hi:[1,0,1]
	v_pk_fma_f32 v[6:7], v[32:33], v[50:51], v[22:23] op_sel:[0,1,0]
	v_pk_fma_f32 v[8:9], v[32:33], v[52:53], v[24:25] op_sel_hi:[1,0,1]
	v_pk_fma_f32 v[10:11], v[32:33], v[52:53], v[26:27] op_sel:[0,1,0]
	v_pk_fma_f32 v[12:13], v[32:33], v[54:55], v[28:29] op_sel_hi:[1,0,1]
	v_pk_fma_f32 v[14:15], v[32:33], v[54:55], v[30:31] op_sel:[0,1,0]
	s_waitcnt lgkmcnt(7)
	v_pk_mul_f32 v[32:33], v[0:1], v[74:75] op_sel_hi:[1,0]
	v_pk_mul_f32 v[36:37], v[0:1], v[64:65] op_sel_hi:[1,0]
	v_pk_fma_f32 v[32:33], v[2:3], v[74:75], v[32:33] op_sel:[0,1,0]
	v_pk_fma_f32 v[36:37], v[2:3], v[64:65], v[36:37] op_sel:[0,1,0]
	v_pk_fma_f32 v[32:33], v[4:5], v[76:77], v[32:33] op_sel_hi:[1,0,1]
	v_pk_fma_f32 v[36:37], v[4:5], v[66:67], v[36:37] op_sel_hi:[1,0,1]
	v_pk_fma_f32 v[32:33], v[6:7], v[76:77], v[32:33] op_sel:[0,1,0]
	v_pk_fma_f32 v[36:37], v[6:7], v[66:67], v[36:37] op_sel:[0,1,0]
	v_pk_fma_f32 v[32:33], v[8:9], v[78:79], v[32:33] op_sel_hi:[1,0,1]
	v_pk_fma_f32 v[36:37], v[8:9], v[68:69], v[36:37] op_sel_hi:[1,0,1]
	v_pk_fma_f32 v[32:33], v[10:11], v[78:79], v[32:33] op_sel:[0,1,0]
	v_pk_fma_f32 v[36:37], v[10:11], v[68:69], v[36:37] op_sel:[0,1,0]
	v_pk_fma_f32 v[32:33], v[12:13], v[80:81], v[32:33] op_sel_hi:[1,0,1]
	v_pk_fma_f32 v[36:37], v[12:13], v[70:71], v[36:37] op_sel_hi:[1,0,1]
	v_pk_fma_f32 v[32:33], v[14:15], v[80:81], v[32:33] op_sel:[0,1,0]
	v_pk_fma_f32 v[36:37], v[14:15], v[70:71], v[36:37] op_sel:[0,1,0]
	ds_write2st64_b32 v134, v36, v37 offset0:8 offset1:9
	ds_read_b128 v[40:43], v132 offset:9568
	ds_read_b128 v[44:47], v132 offset:9584
	ds_read_b128 v[48:51], v132 offset:9824
	ds_read_b128 v[52:55], v132 offset:9840
	ds_read_b128 v[56:59], v132 offset:10080
	ds_read_b128 v[60:63], v132 offset:10096
	ds_read_b128 v[64:67], v132 offset:10336
	ds_read_b128 v[68:71], v132 offset:10352
	ds_read_b64 v[72:73], v133 offset:10592
	s_waitcnt lgkmcnt(10)
	v_add_f32_dpp v32, v32, v32 row_half_mirror row_mask:0xf bank_mask:0xf bound_ctrl:1
	v_add_f32_dpp v33, v33, v33 row_half_mirror row_mask:0xf bank_mask:0xf bound_ctrl:1
	v_pk_fma_f32 v[16:17], v[106:107], v[90:91], v[0:1] op_sel_hi:[1,0,1]
	v_add_f32_dpp v32, v32, v32 quad_perm:[1,0,3,2] row_mask:0xf bank_mask:0xf bound_ctrl:1
	v_add_f32_dpp v33, v33, v33 quad_perm:[1,0,3,2] row_mask:0xf bank_mask:0xf bound_ctrl:1
	v_pk_fma_f32 v[18:19], v[106:107], v[90:91], v[2:3] op_sel:[0,1,0]
	v_add_f32_dpp v32, v32, v32 quad_perm:[2,3,0,1] row_mask:0xf bank_mask:0xf bound_ctrl:1
	v_add_f32_dpp v33, v33, v33 quad_perm:[2,3,0,1] row_mask:0xf bank_mask:0xf bound_ctrl:1
	v_pk_fma_f32 v[20:21], v[106:107], v[92:93], v[4:5] op_sel_hi:[1,0,1]
	v_pk_fma_f32 v[22:23], v[106:107], v[92:93], v[6:7] op_sel:[0,1,0]
	v_pk_fma_f32 v[24:25], v[106:107], v[94:95], v[8:9] op_sel_hi:[1,0,1]
	v_pk_fma_f32 v[26:27], v[106:107], v[94:95], v[10:11] op_sel:[0,1,0]
	v_pk_fma_f32 v[28:29], v[106:107], v[96:97], v[12:13] op_sel_hi:[1,0,1]
	v_pk_fma_f32 v[30:31], v[106:107], v[96:97], v[14:15] op_sel:[0,1,0]
	v_pk_fma_f32 v[0:1], v[32:33], v[82:83], v[16:17] op_sel_hi:[1,0,1]
	v_pk_fma_f32 v[2:3], v[32:33], v[82:83], v[18:19] op_sel:[0,1,0]
	v_pk_fma_f32 v[4:5], v[32:33], v[84:85], v[20:21] op_sel_hi:[1,0,1]
	v_pk_fma_f32 v[6:7], v[32:33], v[84:85], v[22:23] op_sel:[0,1,0]
	v_pk_fma_f32 v[8:9], v[32:33], v[86:87], v[24:25] op_sel_hi:[1,0,1]
	v_pk_fma_f32 v[10:11], v[32:33], v[86:87], v[26:27] op_sel:[0,1,0]
	v_pk_fma_f32 v[12:13], v[32:33], v[88:89], v[28:29] op_sel_hi:[1,0,1]
	v_pk_fma_f32 v[14:15], v[32:33], v[88:89], v[30:31] op_sel:[0,1,0]
	s_waitcnt lgkmcnt(7)
	v_pk_mul_f32 v[32:33], v[0:1], v[40:41] op_sel_hi:[1,0]
	v_pk_mul_f32 v[36:37], v[0:1], v[98:99] op_sel_hi:[1,0]
	v_pk_fma_f32 v[32:33], v[2:3], v[40:41], v[32:33] op_sel:[0,1,0]
	v_pk_fma_f32 v[36:37], v[2:3], v[98:99], v[36:37] op_sel:[0,1,0]
	v_pk_fma_f32 v[32:33], v[4:5], v[42:43], v[32:33] op_sel_hi:[1,0,1]
	v_pk_fma_f32 v[36:37], v[4:5], v[100:101], v[36:37] op_sel_hi:[1,0,1]
	v_pk_fma_f32 v[32:33], v[6:7], v[42:43], v[32:33] op_sel:[0,1,0]
	v_pk_fma_f32 v[36:37], v[6:7], v[100:101], v[36:37] op_sel:[0,1,0]
	v_pk_fma_f32 v[32:33], v[8:9], v[44:45], v[32:33] op_sel_hi:[1,0,1]
	v_pk_fma_f32 v[36:37], v[8:9], v[102:103], v[36:37] op_sel_hi:[1,0,1]
	v_pk_fma_f32 v[32:33], v[10:11], v[44:45], v[32:33] op_sel:[0,1,0]
	v_pk_fma_f32 v[36:37], v[10:11], v[102:103], v[36:37] op_sel:[0,1,0]
	v_pk_fma_f32 v[32:33], v[12:13], v[46:47], v[32:33] op_sel_hi:[1,0,1]
	v_pk_fma_f32 v[36:37], v[12:13], v[104:105], v[36:37] op_sel_hi:[1,0,1]
	v_pk_fma_f32 v[32:33], v[14:15], v[46:47], v[32:33] op_sel:[0,1,0]
	v_pk_fma_f32 v[36:37], v[14:15], v[104:105], v[36:37] op_sel:[0,1,0]
	ds_write2st64_b32 v134, v36, v37 offset0:10 offset1:11
	ds_read_b128 v[74:77], v132 offset:11120
	ds_read_b128 v[78:81], v132 offset:11136
	ds_read_b128 v[82:85], v132 offset:11376
	ds_read_b128 v[86:89], v132 offset:11392
	ds_read_b128 v[90:93], v132 offset:11632
	ds_read_b128 v[94:97], v132 offset:11648
	ds_read_b128 v[98:101], v132 offset:11888
	ds_read_b128 v[102:105], v132 offset:11904
	ds_read_b64 v[106:107], v133 offset:12144
	s_waitcnt lgkmcnt(10)
	v_add_f32_dpp v32, v32, v32 row_half_mirror row_mask:0xf bank_mask:0xf bound_ctrl:1
	v_add_f32_dpp v33, v33, v33 row_half_mirror row_mask:0xf bank_mask:0xf bound_ctrl:1
	v_pk_fma_f32 v[16:17], v[72:73], v[56:57], v[0:1] op_sel_hi:[1,0,1]
	v_add_f32_dpp v32, v32, v32 quad_perm:[1,0,3,2] row_mask:0xf bank_mask:0xf bound_ctrl:1
	v_add_f32_dpp v33, v33, v33 quad_perm:[1,0,3,2] row_mask:0xf bank_mask:0xf bound_ctrl:1
	v_pk_fma_f32 v[18:19], v[72:73], v[56:57], v[2:3] op_sel:[0,1,0]
	v_add_f32_dpp v32, v32, v32 quad_perm:[2,3,0,1] row_mask:0xf bank_mask:0xf bound_ctrl:1
	v_add_f32_dpp v33, v33, v33 quad_perm:[2,3,0,1] row_mask:0xf bank_mask:0xf bound_ctrl:1
	v_pk_fma_f32 v[20:21], v[72:73], v[58:59], v[4:5] op_sel_hi:[1,0,1]
	v_pk_fma_f32 v[22:23], v[72:73], v[58:59], v[6:7] op_sel:[0,1,0]
	v_pk_fma_f32 v[24:25], v[72:73], v[60:61], v[8:9] op_sel_hi:[1,0,1]
	v_pk_fma_f32 v[26:27], v[72:73], v[60:61], v[10:11] op_sel:[0,1,0]
	v_pk_fma_f32 v[28:29], v[72:73], v[62:63], v[12:13] op_sel_hi:[1,0,1]
	v_pk_fma_f32 v[30:31], v[72:73], v[62:63], v[14:15] op_sel:[0,1,0]
	v_pk_fma_f32 v[0:1], v[32:33], v[48:49], v[16:17] op_sel_hi:[1,0,1]
	v_pk_fma_f32 v[2:3], v[32:33], v[48:49], v[18:19] op_sel:[0,1,0]
	v_pk_fma_f32 v[4:5], v[32:33], v[50:51], v[20:21] op_sel_hi:[1,0,1]
	v_pk_fma_f32 v[6:7], v[32:33], v[50:51], v[22:23] op_sel:[0,1,0]
	v_pk_fma_f32 v[8:9], v[32:33], v[52:53], v[24:25] op_sel_hi:[1,0,1]
	v_pk_fma_f32 v[10:11], v[32:33], v[52:53], v[26:27] op_sel:[0,1,0]
	v_pk_fma_f32 v[12:13], v[32:33], v[54:55], v[28:29] op_sel_hi:[1,0,1]
	v_pk_fma_f32 v[14:15], v[32:33], v[54:55], v[30:31] op_sel:[0,1,0]
	s_waitcnt lgkmcnt(7)
	v_pk_mul_f32 v[32:33], v[0:1], v[74:75] op_sel_hi:[1,0]
	v_pk_mul_f32 v[36:37], v[0:1], v[64:65] op_sel_hi:[1,0]
	v_pk_fma_f32 v[32:33], v[2:3], v[74:75], v[32:33] op_sel:[0,1,0]
	v_pk_fma_f32 v[36:37], v[2:3], v[64:65], v[36:37] op_sel:[0,1,0]
	v_pk_fma_f32 v[32:33], v[4:5], v[76:77], v[32:33] op_sel_hi:[1,0,1]
	v_pk_fma_f32 v[36:37], v[4:5], v[66:67], v[36:37] op_sel_hi:[1,0,1]
	v_pk_fma_f32 v[32:33], v[6:7], v[76:77], v[32:33] op_sel:[0,1,0]
	v_pk_fma_f32 v[36:37], v[6:7], v[66:67], v[36:37] op_sel:[0,1,0]
	v_pk_fma_f32 v[32:33], v[8:9], v[78:79], v[32:33] op_sel_hi:[1,0,1]
	v_pk_fma_f32 v[36:37], v[8:9], v[68:69], v[36:37] op_sel_hi:[1,0,1]
	v_pk_fma_f32 v[32:33], v[10:11], v[78:79], v[32:33] op_sel:[0,1,0]
	v_pk_fma_f32 v[36:37], v[10:11], v[68:69], v[36:37] op_sel:[0,1,0]
	v_pk_fma_f32 v[32:33], v[12:13], v[80:81], v[32:33] op_sel_hi:[1,0,1]
	v_pk_fma_f32 v[36:37], v[12:13], v[70:71], v[36:37] op_sel_hi:[1,0,1]
	v_pk_fma_f32 v[32:33], v[14:15], v[80:81], v[32:33] op_sel:[0,1,0]
	v_pk_fma_f32 v[36:37], v[14:15], v[70:71], v[36:37] op_sel:[0,1,0]
	ds_write2st64_b32 v134, v36, v37 offset0:12 offset1:13
	ds_read_b128 v[40:43], v132 offset:12672
	ds_read_b128 v[44:47], v132 offset:12688
	ds_read_b128 v[48:51], v132 offset:12928
	ds_read_b128 v[52:55], v132 offset:12944
	ds_read_b128 v[56:59], v132 offset:13184
	ds_read_b128 v[60:63], v132 offset:13200
	ds_read_b128 v[64:67], v132 offset:13440
	ds_read_b128 v[68:71], v132 offset:13456
	ds_read_b64 v[72:73], v133 offset:13696
	s_waitcnt lgkmcnt(10)
	v_add_f32_dpp v32, v32, v32 row_half_mirror row_mask:0xf bank_mask:0xf bound_ctrl:1
	v_add_f32_dpp v33, v33, v33 row_half_mirror row_mask:0xf bank_mask:0xf bound_ctrl:1
	v_pk_fma_f32 v[16:17], v[106:107], v[90:91], v[0:1] op_sel_hi:[1,0,1]
	v_add_f32_dpp v32, v32, v32 quad_perm:[1,0,3,2] row_mask:0xf bank_mask:0xf bound_ctrl:1
	v_add_f32_dpp v33, v33, v33 quad_perm:[1,0,3,2] row_mask:0xf bank_mask:0xf bound_ctrl:1
	v_pk_fma_f32 v[18:19], v[106:107], v[90:91], v[2:3] op_sel:[0,1,0]
	v_add_f32_dpp v32, v32, v32 quad_perm:[2,3,0,1] row_mask:0xf bank_mask:0xf bound_ctrl:1
	v_add_f32_dpp v33, v33, v33 quad_perm:[2,3,0,1] row_mask:0xf bank_mask:0xf bound_ctrl:1
	v_pk_fma_f32 v[20:21], v[106:107], v[92:93], v[4:5] op_sel_hi:[1,0,1]
	v_pk_fma_f32 v[22:23], v[106:107], v[92:93], v[6:7] op_sel:[0,1,0]
	v_pk_fma_f32 v[24:25], v[106:107], v[94:95], v[8:9] op_sel_hi:[1,0,1]
	v_pk_fma_f32 v[26:27], v[106:107], v[94:95], v[10:11] op_sel:[0,1,0]
	v_pk_fma_f32 v[28:29], v[106:107], v[96:97], v[12:13] op_sel_hi:[1,0,1]
	v_pk_fma_f32 v[30:31], v[106:107], v[96:97], v[14:15] op_sel:[0,1,0]
	v_pk_fma_f32 v[0:1], v[32:33], v[82:83], v[16:17] op_sel_hi:[1,0,1]
	v_pk_fma_f32 v[2:3], v[32:33], v[82:83], v[18:19] op_sel:[0,1,0]
	v_pk_fma_f32 v[4:5], v[32:33], v[84:85], v[20:21] op_sel_hi:[1,0,1]
	v_pk_fma_f32 v[6:7], v[32:33], v[84:85], v[22:23] op_sel:[0,1,0]
	v_pk_fma_f32 v[8:9], v[32:33], v[86:87], v[24:25] op_sel_hi:[1,0,1]
	v_pk_fma_f32 v[10:11], v[32:33], v[86:87], v[26:27] op_sel:[0,1,0]
	v_pk_fma_f32 v[12:13], v[32:33], v[88:89], v[28:29] op_sel_hi:[1,0,1]
	v_pk_fma_f32 v[14:15], v[32:33], v[88:89], v[30:31] op_sel:[0,1,0]
	s_waitcnt lgkmcnt(7)
	v_pk_mul_f32 v[32:33], v[0:1], v[40:41] op_sel_hi:[1,0]
	v_pk_mul_f32 v[36:37], v[0:1], v[98:99] op_sel_hi:[1,0]
	v_pk_fma_f32 v[32:33], v[2:3], v[40:41], v[32:33] op_sel:[0,1,0]
	v_pk_fma_f32 v[36:37], v[2:3], v[98:99], v[36:37] op_sel:[0,1,0]
	v_pk_fma_f32 v[32:33], v[4:5], v[42:43], v[32:33] op_sel_hi:[1,0,1]
	v_pk_fma_f32 v[36:37], v[4:5], v[100:101], v[36:37] op_sel_hi:[1,0,1]
	v_pk_fma_f32 v[32:33], v[6:7], v[42:43], v[32:33] op_sel:[0,1,0]
	v_pk_fma_f32 v[36:37], v[6:7], v[100:101], v[36:37] op_sel:[0,1,0]
	v_pk_fma_f32 v[32:33], v[8:9], v[44:45], v[32:33] op_sel_hi:[1,0,1]
	v_pk_fma_f32 v[36:37], v[8:9], v[102:103], v[36:37] op_sel_hi:[1,0,1]
	v_pk_fma_f32 v[32:33], v[10:11], v[44:45], v[32:33] op_sel:[0,1,0]
	v_pk_fma_f32 v[36:37], v[10:11], v[102:103], v[36:37] op_sel:[0,1,0]
	v_pk_fma_f32 v[32:33], v[12:13], v[46:47], v[32:33] op_sel_hi:[1,0,1]
	v_pk_fma_f32 v[36:37], v[12:13], v[104:105], v[36:37] op_sel_hi:[1,0,1]
	v_pk_fma_f32 v[32:33], v[14:15], v[46:47], v[32:33] op_sel:[0,1,0]
	v_pk_fma_f32 v[36:37], v[14:15], v[104:105], v[36:37] op_sel:[0,1,0]
	ds_write2st64_b32 v134, v36, v37 offset0:14 offset1:15
	ds_read_b128 v[74:77], v132 offset:14224
	ds_read_b128 v[78:81], v132 offset:14240
	ds_read_b128 v[82:85], v132 offset:14480
	ds_read_b128 v[86:89], v132 offset:14496
	ds_read_b128 v[90:93], v132 offset:14736
	ds_read_b128 v[94:97], v132 offset:14752
	ds_read_b128 v[98:101], v132 offset:14992
	ds_read_b128 v[102:105], v132 offset:15008
	ds_read_b64 v[106:107], v133 offset:15248
	ds_read_b128 v[116:119], v135
	ds_read_b128 v[120:123], v135 offset:16
	ds_read_b128 v[124:127], v135 offset:2048
	ds_read_b128 v[128:131], v135 offset:2064
	s_waitcnt lgkmcnt(14)
	v_add_f32_dpp v32, v32, v32 row_half_mirror row_mask:0xf bank_mask:0xf bound_ctrl:1
	v_add_f32_dpp v33, v33, v33 row_half_mirror row_mask:0xf bank_mask:0xf bound_ctrl:1
	v_pk_fma_f32 v[16:17], v[72:73], v[56:57], v[0:1] op_sel_hi:[1,0,1]
	v_add_f32_dpp v32, v32, v32 quad_perm:[1,0,3,2] row_mask:0xf bank_mask:0xf bound_ctrl:1
	v_add_f32_dpp v33, v33, v33 quad_perm:[1,0,3,2] row_mask:0xf bank_mask:0xf bound_ctrl:1
	v_pk_fma_f32 v[18:19], v[72:73], v[56:57], v[2:3] op_sel:[0,1,0]
	v_add_f32_dpp v32, v32, v32 quad_perm:[2,3,0,1] row_mask:0xf bank_mask:0xf bound_ctrl:1
	v_add_f32_dpp v33, v33, v33 quad_perm:[2,3,0,1] row_mask:0xf bank_mask:0xf bound_ctrl:1
	v_pk_fma_f32 v[20:21], v[72:73], v[58:59], v[4:5] op_sel_hi:[1,0,1]
	v_pk_fma_f32 v[22:23], v[72:73], v[58:59], v[6:7] op_sel:[0,1,0]
	v_pk_fma_f32 v[24:25], v[72:73], v[60:61], v[8:9] op_sel_hi:[1,0,1]
	v_pk_fma_f32 v[26:27], v[72:73], v[60:61], v[10:11] op_sel:[0,1,0]
	v_pk_fma_f32 v[28:29], v[72:73], v[62:63], v[12:13] op_sel_hi:[1,0,1]
	v_pk_fma_f32 v[30:31], v[72:73], v[62:63], v[14:15] op_sel:[0,1,0]
	v_pk_fma_f32 v[0:1], v[32:33], v[48:49], v[16:17] op_sel_hi:[1,0,1]
	v_pk_fma_f32 v[2:3], v[32:33], v[48:49], v[18:19] op_sel:[0,1,0]
	v_pk_fma_f32 v[4:5], v[32:33], v[50:51], v[20:21] op_sel_hi:[1,0,1]
	v_pk_fma_f32 v[6:7], v[32:33], v[50:51], v[22:23] op_sel:[0,1,0]
	v_pk_fma_f32 v[8:9], v[32:33], v[52:53], v[24:25] op_sel_hi:[1,0,1]
	v_pk_fma_f32 v[10:11], v[32:33], v[52:53], v[26:27] op_sel:[0,1,0]
	v_pk_fma_f32 v[12:13], v[32:33], v[54:55], v[28:29] op_sel_hi:[1,0,1]
	v_pk_fma_f32 v[14:15], v[32:33], v[54:55], v[30:31] op_sel:[0,1,0]
	s_waitcnt lgkmcnt(0)
	v_pk_add_f32 v[116:117], v[116:117], v[118:119]
	v_pk_add_f32 v[120:121], v[120:121], v[122:123]
	v_pk_add_f32 v[124:125], v[124:125], v[126:127]
	v_pk_add_f32 v[128:129], v[128:129], v[130:131]
	v_pk_add_f32 v[116:117], v[116:117], v[120:121]
	v_pk_add_f32 v[124:125], v[124:125], v[128:129]
	v_add_f32_e32 v116, v116, v117
	v_add_f32_e32 v124, v124, v125
	global_atomic_add_f32 v[136:137], v116, off
	global_atomic_add_f32 v[138:139], v124, off
	v_lshl_add_u64 v[136:137], v[136:137], 0, s[38:39]
	v_lshl_add_u64 v[138:139], v[138:139], 0, s[38:39]
	s_waitcnt lgkmcnt(7)
	v_pk_mul_f32 v[32:33], v[0:1], v[74:75] op_sel_hi:[1,0]
	v_pk_mul_f32 v[36:37], v[0:1], v[64:65] op_sel_hi:[1,0]
	v_pk_fma_f32 v[32:33], v[2:3], v[74:75], v[32:33] op_sel:[0,1,0]
	v_pk_fma_f32 v[36:37], v[2:3], v[64:65], v[36:37] op_sel:[0,1,0]
	v_pk_fma_f32 v[32:33], v[4:5], v[76:77], v[32:33] op_sel_hi:[1,0,1]
	v_pk_fma_f32 v[36:37], v[4:5], v[66:67], v[36:37] op_sel_hi:[1,0,1]
	v_pk_fma_f32 v[32:33], v[6:7], v[76:77], v[32:33] op_sel:[0,1,0]
	v_pk_fma_f32 v[36:37], v[6:7], v[66:67], v[36:37] op_sel:[0,1,0]
	v_pk_fma_f32 v[32:33], v[8:9], v[78:79], v[32:33] op_sel_hi:[1,0,1]
	v_pk_fma_f32 v[36:37], v[8:9], v[68:69], v[36:37] op_sel_hi:[1,0,1]
	v_pk_fma_f32 v[32:33], v[10:11], v[78:79], v[32:33] op_sel:[0,1,0]
	v_pk_fma_f32 v[36:37], v[10:11], v[68:69], v[36:37] op_sel:[0,1,0]
	v_pk_fma_f32 v[32:33], v[12:13], v[80:81], v[32:33] op_sel_hi:[1,0,1]
	v_pk_fma_f32 v[36:37], v[12:13], v[70:71], v[36:37] op_sel_hi:[1,0,1]
	v_pk_fma_f32 v[32:33], v[14:15], v[80:81], v[32:33] op_sel:[0,1,0]
	v_pk_fma_f32 v[36:37], v[14:15], v[70:71], v[36:37] op_sel:[0,1,0]
	ds_write2st64_b32 v134, v36, v37 offset0:0 offset1:1
	ds_read_b128 v[40:43], v132 offset:15776
	ds_read_b128 v[44:47], v132 offset:15792
	ds_read_b128 v[48:51], v132 offset:16032
	ds_read_b128 v[52:55], v132 offset:16048
	ds_read_b128 v[56:59], v132 offset:16288
	ds_read_b128 v[60:63], v132 offset:16304
	ds_read_b128 v[64:67], v132 offset:16544
	ds_read_b128 v[68:71], v132 offset:16560
	ds_read_b64 v[72:73], v133 offset:16800
	s_waitcnt lgkmcnt(10)
	v_add_f32_dpp v32, v32, v32 row_half_mirror row_mask:0xf bank_mask:0xf bound_ctrl:1
	v_add_f32_dpp v33, v33, v33 row_half_mirror row_mask:0xf bank_mask:0xf bound_ctrl:1
	v_pk_fma_f32 v[16:17], v[106:107], v[90:91], v[0:1] op_sel_hi:[1,0,1]
	v_add_f32_dpp v32, v32, v32 quad_perm:[1,0,3,2] row_mask:0xf bank_mask:0xf bound_ctrl:1
	v_add_f32_dpp v33, v33, v33 quad_perm:[1,0,3,2] row_mask:0xf bank_mask:0xf bound_ctrl:1
	v_pk_fma_f32 v[18:19], v[106:107], v[90:91], v[2:3] op_sel:[0,1,0]
	v_add_f32_dpp v32, v32, v32 quad_perm:[2,3,0,1] row_mask:0xf bank_mask:0xf bound_ctrl:1
	v_add_f32_dpp v33, v33, v33 quad_perm:[2,3,0,1] row_mask:0xf bank_mask:0xf bound_ctrl:1
	v_pk_fma_f32 v[20:21], v[106:107], v[92:93], v[4:5] op_sel_hi:[1,0,1]
	v_pk_fma_f32 v[22:23], v[106:107], v[92:93], v[6:7] op_sel:[0,1,0]
	v_pk_fma_f32 v[24:25], v[106:107], v[94:95], v[8:9] op_sel_hi:[1,0,1]
	v_pk_fma_f32 v[26:27], v[106:107], v[94:95], v[10:11] op_sel:[0,1,0]
	v_pk_fma_f32 v[28:29], v[106:107], v[96:97], v[12:13] op_sel_hi:[1,0,1]
	v_pk_fma_f32 v[30:31], v[106:107], v[96:97], v[14:15] op_sel:[0,1,0]
	v_pk_fma_f32 v[0:1], v[32:33], v[82:83], v[16:17] op_sel_hi:[1,0,1]
	v_pk_fma_f32 v[2:3], v[32:33], v[82:83], v[18:19] op_sel:[0,1,0]
	v_pk_fma_f32 v[4:5], v[32:33], v[84:85], v[20:21] op_sel_hi:[1,0,1]
	v_pk_fma_f32 v[6:7], v[32:33], v[84:85], v[22:23] op_sel:[0,1,0]
	v_pk_fma_f32 v[8:9], v[32:33], v[86:87], v[24:25] op_sel_hi:[1,0,1]
	v_pk_fma_f32 v[10:11], v[32:33], v[86:87], v[26:27] op_sel:[0,1,0]
	v_pk_fma_f32 v[12:13], v[32:33], v[88:89], v[28:29] op_sel_hi:[1,0,1]
	v_pk_fma_f32 v[14:15], v[32:33], v[88:89], v[30:31] op_sel:[0,1,0]
	s_waitcnt lgkmcnt(7)
	v_pk_mul_f32 v[32:33], v[0:1], v[40:41] op_sel_hi:[1,0]
	v_pk_mul_f32 v[36:37], v[0:1], v[98:99] op_sel_hi:[1,0]
	v_pk_fma_f32 v[32:33], v[2:3], v[40:41], v[32:33] op_sel:[0,1,0]
	v_pk_fma_f32 v[36:37], v[2:3], v[98:99], v[36:37] op_sel:[0,1,0]
	v_pk_fma_f32 v[32:33], v[4:5], v[42:43], v[32:33] op_sel_hi:[1,0,1]
	v_pk_fma_f32 v[36:37], v[4:5], v[100:101], v[36:37] op_sel_hi:[1,0,1]
	v_pk_fma_f32 v[32:33], v[6:7], v[42:43], v[32:33] op_sel:[0,1,0]
	v_pk_fma_f32 v[36:37], v[6:7], v[100:101], v[36:37] op_sel:[0,1,0]
	v_pk_fma_f32 v[32:33], v[8:9], v[44:45], v[32:33] op_sel_hi:[1,0,1]
	v_pk_fma_f32 v[36:37], v[8:9], v[102:103], v[36:37] op_sel_hi:[1,0,1]
	v_pk_fma_f32 v[32:33], v[10:11], v[44:45], v[32:33] op_sel:[0,1,0]
	v_pk_fma_f32 v[36:37], v[10:11], v[102:103], v[36:37] op_sel:[0,1,0]
	v_pk_fma_f32 v[32:33], v[12:13], v[46:47], v[32:33] op_sel_hi:[1,0,1]
	v_pk_fma_f32 v[36:37], v[12:13], v[104:105], v[36:37] op_sel_hi:[1,0,1]
	v_pk_fma_f32 v[32:33], v[14:15], v[46:47], v[32:33] op_sel:[0,1,0]
	v_pk_fma_f32 v[36:37], v[14:15], v[104:105], v[36:37] op_sel:[0,1,0]
	ds_write2st64_b32 v134, v36, v37 offset0:2 offset1:3
	ds_read_b128 v[74:77], v132 offset:17328
	ds_read_b128 v[78:81], v132 offset:17344
	ds_read_b128 v[82:85], v132 offset:17584
	ds_read_b128 v[86:89], v132 offset:17600
	ds_read_b128 v[90:93], v132 offset:17840
	ds_read_b128 v[94:97], v132 offset:17856
	ds_read_b128 v[98:101], v132 offset:18096
	ds_read_b128 v[102:105], v132 offset:18112
	ds_read_b64 v[106:107], v133 offset:18352
	s_waitcnt lgkmcnt(10)
	v_add_f32_dpp v32, v32, v32 row_half_mirror row_mask:0xf bank_mask:0xf bound_ctrl:1
	v_add_f32_dpp v33, v33, v33 row_half_mirror row_mask:0xf bank_mask:0xf bound_ctrl:1
	v_pk_fma_f32 v[16:17], v[72:73], v[56:57], v[0:1] op_sel_hi:[1,0,1]
	v_add_f32_dpp v32, v32, v32 quad_perm:[1,0,3,2] row_mask:0xf bank_mask:0xf bound_ctrl:1
	v_add_f32_dpp v33, v33, v33 quad_perm:[1,0,3,2] row_mask:0xf bank_mask:0xf bound_ctrl:1
	v_pk_fma_f32 v[18:19], v[72:73], v[56:57], v[2:3] op_sel:[0,1,0]
	v_add_f32_dpp v32, v32, v32 quad_perm:[2,3,0,1] row_mask:0xf bank_mask:0xf bound_ctrl:1
	v_add_f32_dpp v33, v33, v33 quad_perm:[2,3,0,1] row_mask:0xf bank_mask:0xf bound_ctrl:1
	v_pk_fma_f32 v[20:21], v[72:73], v[58:59], v[4:5] op_sel_hi:[1,0,1]
	v_pk_fma_f32 v[22:23], v[72:73], v[58:59], v[6:7] op_sel:[0,1,0]
	v_pk_fma_f32 v[24:25], v[72:73], v[60:61], v[8:9] op_sel_hi:[1,0,1]
	v_pk_fma_f32 v[26:27], v[72:73], v[60:61], v[10:11] op_sel:[0,1,0]
	v_pk_fma_f32 v[28:29], v[72:73], v[62:63], v[12:13] op_sel_hi:[1,0,1]
	v_pk_fma_f32 v[30:31], v[72:73], v[62:63], v[14:15] op_sel:[0,1,0]
	v_pk_fma_f32 v[0:1], v[32:33], v[48:49], v[16:17] op_sel_hi:[1,0,1]
	v_pk_fma_f32 v[2:3], v[32:33], v[48:49], v[18:19] op_sel:[0,1,0]
	v_pk_fma_f32 v[4:5], v[32:33], v[50:51], v[20:21] op_sel_hi:[1,0,1]
	v_pk_fma_f32 v[6:7], v[32:33], v[50:51], v[22:23] op_sel:[0,1,0]
	v_pk_fma_f32 v[8:9], v[32:33], v[52:53], v[24:25] op_sel_hi:[1,0,1]
	v_pk_fma_f32 v[10:11], v[32:33], v[52:53], v[26:27] op_sel:[0,1,0]
	v_pk_fma_f32 v[12:13], v[32:33], v[54:55], v[28:29] op_sel_hi:[1,0,1]
	v_pk_fma_f32 v[14:15], v[32:33], v[54:55], v[30:31] op_sel:[0,1,0]
	s_waitcnt lgkmcnt(7)
	v_pk_mul_f32 v[32:33], v[0:1], v[74:75] op_sel_hi:[1,0]
	v_pk_mul_f32 v[36:37], v[0:1], v[64:65] op_sel_hi:[1,0]
	v_pk_fma_f32 v[32:33], v[2:3], v[74:75], v[32:33] op_sel:[0,1,0]
	v_pk_fma_f32 v[36:37], v[2:3], v[64:65], v[36:37] op_sel:[0,1,0]
	v_pk_fma_f32 v[32:33], v[4:5], v[76:77], v[32:33] op_sel_hi:[1,0,1]
	v_pk_fma_f32 v[36:37], v[4:5], v[66:67], v[36:37] op_sel_hi:[1,0,1]
	v_pk_fma_f32 v[32:33], v[6:7], v[76:77], v[32:33] op_sel:[0,1,0]
	v_pk_fma_f32 v[36:37], v[6:7], v[66:67], v[36:37] op_sel:[0,1,0]
	v_pk_fma_f32 v[32:33], v[8:9], v[78:79], v[32:33] op_sel_hi:[1,0,1]
	v_pk_fma_f32 v[36:37], v[8:9], v[68:69], v[36:37] op_sel_hi:[1,0,1]
	v_pk_fma_f32 v[32:33], v[10:11], v[78:79], v[32:33] op_sel:[0,1,0]
	v_pk_fma_f32 v[36:37], v[10:11], v[68:69], v[36:37] op_sel:[0,1,0]
	v_pk_fma_f32 v[32:33], v[12:13], v[80:81], v[32:33] op_sel_hi:[1,0,1]
	v_pk_fma_f32 v[36:37], v[12:13], v[70:71], v[36:37] op_sel_hi:[1,0,1]
	v_pk_fma_f32 v[32:33], v[14:15], v[80:81], v[32:33] op_sel:[0,1,0]
	v_pk_fma_f32 v[36:37], v[14:15], v[70:71], v[36:37] op_sel:[0,1,0]
	ds_write2st64_b32 v134, v36, v37 offset0:4 offset1:5
	ds_read_b128 v[40:43], v132 offset:18880
	ds_read_b128 v[44:47], v132 offset:18896
	ds_read_b128 v[48:51], v132 offset:19136
	ds_read_b128 v[52:55], v132 offset:19152
	ds_read_b128 v[56:59], v132 offset:19392
	ds_read_b128 v[60:63], v132 offset:19408
	ds_read_b128 v[64:67], v132 offset:19648
	ds_read_b128 v[68:71], v132 offset:19664
	ds_read_b64 v[72:73], v133 offset:19904
	s_waitcnt lgkmcnt(10)
	v_add_f32_dpp v32, v32, v32 row_half_mirror row_mask:0xf bank_mask:0xf bound_ctrl:1
	v_add_f32_dpp v33, v33, v33 row_half_mirror row_mask:0xf bank_mask:0xf bound_ctrl:1
	v_pk_fma_f32 v[16:17], v[106:107], v[90:91], v[0:1] op_sel_hi:[1,0,1]
	v_add_f32_dpp v32, v32, v32 quad_perm:[1,0,3,2] row_mask:0xf bank_mask:0xf bound_ctrl:1
	v_add_f32_dpp v33, v33, v33 quad_perm:[1,0,3,2] row_mask:0xf bank_mask:0xf bound_ctrl:1
	v_pk_fma_f32 v[18:19], v[106:107], v[90:91], v[2:3] op_sel:[0,1,0]
	v_add_f32_dpp v32, v32, v32 quad_perm:[2,3,0,1] row_mask:0xf bank_mask:0xf bound_ctrl:1
	v_add_f32_dpp v33, v33, v33 quad_perm:[2,3,0,1] row_mask:0xf bank_mask:0xf bound_ctrl:1
	v_pk_fma_f32 v[20:21], v[106:107], v[92:93], v[4:5] op_sel_hi:[1,0,1]
	v_pk_fma_f32 v[22:23], v[106:107], v[92:93], v[6:7] op_sel:[0,1,0]
	v_pk_fma_f32 v[24:25], v[106:107], v[94:95], v[8:9] op_sel_hi:[1,0,1]
	v_pk_fma_f32 v[26:27], v[106:107], v[94:95], v[10:11] op_sel:[0,1,0]
	v_pk_fma_f32 v[28:29], v[106:107], v[96:97], v[12:13] op_sel_hi:[1,0,1]
	v_pk_fma_f32 v[30:31], v[106:107], v[96:97], v[14:15] op_sel:[0,1,0]
	v_pk_fma_f32 v[0:1], v[32:33], v[82:83], v[16:17] op_sel_hi:[1,0,1]
	v_pk_fma_f32 v[2:3], v[32:33], v[82:83], v[18:19] op_sel:[0,1,0]
	v_pk_fma_f32 v[4:5], v[32:33], v[84:85], v[20:21] op_sel_hi:[1,0,1]
	v_pk_fma_f32 v[6:7], v[32:33], v[84:85], v[22:23] op_sel:[0,1,0]
	v_pk_fma_f32 v[8:9], v[32:33], v[86:87], v[24:25] op_sel_hi:[1,0,1]
	v_pk_fma_f32 v[10:11], v[32:33], v[86:87], v[26:27] op_sel:[0,1,0]
	v_pk_fma_f32 v[12:13], v[32:33], v[88:89], v[28:29] op_sel_hi:[1,0,1]
	v_pk_fma_f32 v[14:15], v[32:33], v[88:89], v[30:31] op_sel:[0,1,0]
	s_waitcnt lgkmcnt(7)
	v_pk_mul_f32 v[32:33], v[0:1], v[40:41] op_sel_hi:[1,0]
	v_pk_mul_f32 v[36:37], v[0:1], v[98:99] op_sel_hi:[1,0]
	v_pk_fma_f32 v[32:33], v[2:3], v[40:41], v[32:33] op_sel:[0,1,0]
	v_pk_fma_f32 v[36:37], v[2:3], v[98:99], v[36:37] op_sel:[0,1,0]
	v_pk_fma_f32 v[32:33], v[4:5], v[42:43], v[32:33] op_sel_hi:[1,0,1]
	v_pk_fma_f32 v[36:37], v[4:5], v[100:101], v[36:37] op_sel_hi:[1,0,1]
	v_pk_fma_f32 v[32:33], v[6:7], v[42:43], v[32:33] op_sel:[0,1,0]
	v_pk_fma_f32 v[36:37], v[6:7], v[100:101], v[36:37] op_sel:[0,1,0]
	v_pk_fma_f32 v[32:33], v[8:9], v[44:45], v[32:33] op_sel_hi:[1,0,1]
	v_pk_fma_f32 v[36:37], v[8:9], v[102:103], v[36:37] op_sel_hi:[1,0,1]
	v_pk_fma_f32 v[32:33], v[10:11], v[44:45], v[32:33] op_sel:[0,1,0]
	v_pk_fma_f32 v[36:37], v[10:11], v[102:103], v[36:37] op_sel:[0,1,0]
	v_pk_fma_f32 v[32:33], v[12:13], v[46:47], v[32:33] op_sel_hi:[1,0,1]
	v_pk_fma_f32 v[36:37], v[12:13], v[104:105], v[36:37] op_sel_hi:[1,0,1]
	v_pk_fma_f32 v[32:33], v[14:15], v[46:47], v[32:33] op_sel:[0,1,0]
	v_pk_fma_f32 v[36:37], v[14:15], v[104:105], v[36:37] op_sel:[0,1,0]
	ds_write2st64_b32 v134, v36, v37 offset0:6 offset1:7
	ds_read_b128 v[74:77], v132 offset:20432
	ds_read_b128 v[78:81], v132 offset:20448
	ds_read_b128 v[82:85], v132 offset:20688
	ds_read_b128 v[86:89], v132 offset:20704
	ds_read_b128 v[90:93], v132 offset:20944
	ds_read_b128 v[94:97], v132 offset:20960
	ds_read_b128 v[98:101], v132 offset:21200
	ds_read_b128 v[102:105], v132 offset:21216
	ds_read_b64 v[106:107], v133 offset:21456
	s_waitcnt lgkmcnt(10)
	v_add_f32_dpp v32, v32, v32 row_half_mirror row_mask:0xf bank_mask:0xf bound_ctrl:1
	v_add_f32_dpp v33, v33, v33 row_half_mirror row_mask:0xf bank_mask:0xf bound_ctrl:1
	v_pk_fma_f32 v[16:17], v[72:73], v[56:57], v[0:1] op_sel_hi:[1,0,1]
	v_add_f32_dpp v32, v32, v32 quad_perm:[1,0,3,2] row_mask:0xf bank_mask:0xf bound_ctrl:1
	v_add_f32_dpp v33, v33, v33 quad_perm:[1,0,3,2] row_mask:0xf bank_mask:0xf bound_ctrl:1
	v_pk_fma_f32 v[18:19], v[72:73], v[56:57], v[2:3] op_sel:[0,1,0]
	v_add_f32_dpp v32, v32, v32 quad_perm:[2,3,0,1] row_mask:0xf bank_mask:0xf bound_ctrl:1
	v_add_f32_dpp v33, v33, v33 quad_perm:[2,3,0,1] row_mask:0xf bank_mask:0xf bound_ctrl:1
	v_pk_fma_f32 v[20:21], v[72:73], v[58:59], v[4:5] op_sel_hi:[1,0,1]
	v_pk_fma_f32 v[22:23], v[72:73], v[58:59], v[6:7] op_sel:[0,1,0]
	v_pk_fma_f32 v[24:25], v[72:73], v[60:61], v[8:9] op_sel_hi:[1,0,1]
	v_pk_fma_f32 v[26:27], v[72:73], v[60:61], v[10:11] op_sel:[0,1,0]
	v_pk_fma_f32 v[28:29], v[72:73], v[62:63], v[12:13] op_sel_hi:[1,0,1]
	v_pk_fma_f32 v[30:31], v[72:73], v[62:63], v[14:15] op_sel:[0,1,0]
	v_pk_fma_f32 v[0:1], v[32:33], v[48:49], v[16:17] op_sel_hi:[1,0,1]
	v_pk_fma_f32 v[2:3], v[32:33], v[48:49], v[18:19] op_sel:[0,1,0]
	v_pk_fma_f32 v[4:5], v[32:33], v[50:51], v[20:21] op_sel_hi:[1,0,1]
	v_pk_fma_f32 v[6:7], v[32:33], v[50:51], v[22:23] op_sel:[0,1,0]
	v_pk_fma_f32 v[8:9], v[32:33], v[52:53], v[24:25] op_sel_hi:[1,0,1]
	v_pk_fma_f32 v[10:11], v[32:33], v[52:53], v[26:27] op_sel:[0,1,0]
	v_pk_fma_f32 v[12:13], v[32:33], v[54:55], v[28:29] op_sel_hi:[1,0,1]
	v_pk_fma_f32 v[14:15], v[32:33], v[54:55], v[30:31] op_sel:[0,1,0]
	s_waitcnt lgkmcnt(7)
	v_pk_mul_f32 v[32:33], v[0:1], v[74:75] op_sel_hi:[1,0]
	v_pk_mul_f32 v[36:37], v[0:1], v[64:65] op_sel_hi:[1,0]
	v_pk_fma_f32 v[32:33], v[2:3], v[74:75], v[32:33] op_sel:[0,1,0]
	v_pk_fma_f32 v[36:37], v[2:3], v[64:65], v[36:37] op_sel:[0,1,0]
	v_pk_fma_f32 v[32:33], v[4:5], v[76:77], v[32:33] op_sel_hi:[1,0,1]
	v_pk_fma_f32 v[36:37], v[4:5], v[66:67], v[36:37] op_sel_hi:[1,0,1]
	v_pk_fma_f32 v[32:33], v[6:7], v[76:77], v[32:33] op_sel:[0,1,0]
	v_pk_fma_f32 v[36:37], v[6:7], v[66:67], v[36:37] op_sel:[0,1,0]
	v_pk_fma_f32 v[32:33], v[8:9], v[78:79], v[32:33] op_sel_hi:[1,0,1]
	v_pk_fma_f32 v[36:37], v[8:9], v[68:69], v[36:37] op_sel_hi:[1,0,1]
	v_pk_fma_f32 v[32:33], v[10:11], v[78:79], v[32:33] op_sel:[0,1,0]
	v_pk_fma_f32 v[36:37], v[10:11], v[68:69], v[36:37] op_sel:[0,1,0]
	v_pk_fma_f32 v[32:33], v[12:13], v[80:81], v[32:33] op_sel_hi:[1,0,1]
	v_pk_fma_f32 v[36:37], v[12:13], v[70:71], v[36:37] op_sel_hi:[1,0,1]
	v_pk_fma_f32 v[32:33], v[14:15], v[80:81], v[32:33] op_sel:[0,1,0]
	v_pk_fma_f32 v[36:37], v[14:15], v[70:71], v[36:37] op_sel:[0,1,0]
	ds_write2st64_b32 v134, v36, v37 offset0:8 offset1:9
	ds_read_b128 v[40:43], v132 offset:21984
	ds_read_b128 v[44:47], v132 offset:22000
	ds_read_b128 v[48:51], v132 offset:22240
	ds_read_b128 v[52:55], v132 offset:22256
	ds_read_b128 v[56:59], v132 offset:22496
	ds_read_b128 v[60:63], v132 offset:22512
	ds_read_b128 v[64:67], v132 offset:22752
	ds_read_b128 v[68:71], v132 offset:22768
	ds_read_b64 v[72:73], v133 offset:23008
	s_waitcnt lgkmcnt(10)
	v_add_f32_dpp v32, v32, v32 row_half_mirror row_mask:0xf bank_mask:0xf bound_ctrl:1
	v_add_f32_dpp v33, v33, v33 row_half_mirror row_mask:0xf bank_mask:0xf bound_ctrl:1
	v_pk_fma_f32 v[16:17], v[106:107], v[90:91], v[0:1] op_sel_hi:[1,0,1]
	v_add_f32_dpp v32, v32, v32 quad_perm:[1,0,3,2] row_mask:0xf bank_mask:0xf bound_ctrl:1
	v_add_f32_dpp v33, v33, v33 quad_perm:[1,0,3,2] row_mask:0xf bank_mask:0xf bound_ctrl:1
	v_pk_fma_f32 v[18:19], v[106:107], v[90:91], v[2:3] op_sel:[0,1,0]
	v_add_f32_dpp v32, v32, v32 quad_perm:[2,3,0,1] row_mask:0xf bank_mask:0xf bound_ctrl:1
	v_add_f32_dpp v33, v33, v33 quad_perm:[2,3,0,1] row_mask:0xf bank_mask:0xf bound_ctrl:1
	v_pk_fma_f32 v[20:21], v[106:107], v[92:93], v[4:5] op_sel_hi:[1,0,1]
	v_pk_fma_f32 v[22:23], v[106:107], v[92:93], v[6:7] op_sel:[0,1,0]
	v_pk_fma_f32 v[24:25], v[106:107], v[94:95], v[8:9] op_sel_hi:[1,0,1]
	v_pk_fma_f32 v[26:27], v[106:107], v[94:95], v[10:11] op_sel:[0,1,0]
	v_pk_fma_f32 v[28:29], v[106:107], v[96:97], v[12:13] op_sel_hi:[1,0,1]
	v_pk_fma_f32 v[30:31], v[106:107], v[96:97], v[14:15] op_sel:[0,1,0]
	v_pk_fma_f32 v[0:1], v[32:33], v[82:83], v[16:17] op_sel_hi:[1,0,1]
	v_pk_fma_f32 v[2:3], v[32:33], v[82:83], v[18:19] op_sel:[0,1,0]
	v_pk_fma_f32 v[4:5], v[32:33], v[84:85], v[20:21] op_sel_hi:[1,0,1]
	v_pk_fma_f32 v[6:7], v[32:33], v[84:85], v[22:23] op_sel:[0,1,0]
	v_pk_fma_f32 v[8:9], v[32:33], v[86:87], v[24:25] op_sel_hi:[1,0,1]
	v_pk_fma_f32 v[10:11], v[32:33], v[86:87], v[26:27] op_sel:[0,1,0]
	v_pk_fma_f32 v[12:13], v[32:33], v[88:89], v[28:29] op_sel_hi:[1,0,1]
	v_pk_fma_f32 v[14:15], v[32:33], v[88:89], v[30:31] op_sel:[0,1,0]
	s_waitcnt lgkmcnt(7)
	v_pk_mul_f32 v[32:33], v[0:1], v[40:41] op_sel_hi:[1,0]
	v_pk_mul_f32 v[36:37], v[0:1], v[98:99] op_sel_hi:[1,0]
	v_pk_fma_f32 v[32:33], v[2:3], v[40:41], v[32:33] op_sel:[0,1,0]
	v_pk_fma_f32 v[36:37], v[2:3], v[98:99], v[36:37] op_sel:[0,1,0]
	v_pk_fma_f32 v[32:33], v[4:5], v[42:43], v[32:33] op_sel_hi:[1,0,1]
	v_pk_fma_f32 v[36:37], v[4:5], v[100:101], v[36:37] op_sel_hi:[1,0,1]
	v_pk_fma_f32 v[32:33], v[6:7], v[42:43], v[32:33] op_sel:[0,1,0]
	v_pk_fma_f32 v[36:37], v[6:7], v[100:101], v[36:37] op_sel:[0,1,0]
	v_pk_fma_f32 v[32:33], v[8:9], v[44:45], v[32:33] op_sel_hi:[1,0,1]
	v_pk_fma_f32 v[36:37], v[8:9], v[102:103], v[36:37] op_sel_hi:[1,0,1]
	v_pk_fma_f32 v[32:33], v[10:11], v[44:45], v[32:33] op_sel:[0,1,0]
	v_pk_fma_f32 v[36:37], v[10:11], v[102:103], v[36:37] op_sel:[0,1,0]
	v_pk_fma_f32 v[32:33], v[12:13], v[46:47], v[32:33] op_sel_hi:[1,0,1]
	v_pk_fma_f32 v[36:37], v[12:13], v[104:105], v[36:37] op_sel_hi:[1,0,1]
	v_pk_fma_f32 v[32:33], v[14:15], v[46:47], v[32:33] op_sel:[0,1,0]
	v_pk_fma_f32 v[36:37], v[14:15], v[104:105], v[36:37] op_sel:[0,1,0]
	ds_write2st64_b32 v134, v36, v37 offset0:10 offset1:11
	ds_read_b128 v[74:77], v132 offset:23536
	ds_read_b128 v[78:81], v132 offset:23552
	ds_read_b128 v[82:85], v132 offset:23792
	ds_read_b128 v[86:89], v132 offset:23808
	ds_read_b128 v[90:93], v132 offset:24048
	ds_read_b128 v[94:97], v132 offset:24064
	ds_read_b128 v[98:101], v132 offset:24304
	ds_read_b128 v[102:105], v132 offset:24320
	ds_read_b64 v[106:107], v133 offset:24560
	s_waitcnt lgkmcnt(10)
	v_add_f32_dpp v32, v32, v32 row_half_mirror row_mask:0xf bank_mask:0xf bound_ctrl:1
	v_add_f32_dpp v33, v33, v33 row_half_mirror row_mask:0xf bank_mask:0xf bound_ctrl:1
	v_pk_fma_f32 v[16:17], v[72:73], v[56:57], v[0:1] op_sel_hi:[1,0,1]
	v_add_f32_dpp v32, v32, v32 quad_perm:[1,0,3,2] row_mask:0xf bank_mask:0xf bound_ctrl:1
	v_add_f32_dpp v33, v33, v33 quad_perm:[1,0,3,2] row_mask:0xf bank_mask:0xf bound_ctrl:1
	v_pk_fma_f32 v[18:19], v[72:73], v[56:57], v[2:3] op_sel:[0,1,0]
	v_add_f32_dpp v32, v32, v32 quad_perm:[2,3,0,1] row_mask:0xf bank_mask:0xf bound_ctrl:1
	v_add_f32_dpp v33, v33, v33 quad_perm:[2,3,0,1] row_mask:0xf bank_mask:0xf bound_ctrl:1
	v_pk_fma_f32 v[20:21], v[72:73], v[58:59], v[4:5] op_sel_hi:[1,0,1]
	v_pk_fma_f32 v[22:23], v[72:73], v[58:59], v[6:7] op_sel:[0,1,0]
	v_pk_fma_f32 v[24:25], v[72:73], v[60:61], v[8:9] op_sel_hi:[1,0,1]
	v_pk_fma_f32 v[26:27], v[72:73], v[60:61], v[10:11] op_sel:[0,1,0]
	v_pk_fma_f32 v[28:29], v[72:73], v[62:63], v[12:13] op_sel_hi:[1,0,1]
	v_pk_fma_f32 v[30:31], v[72:73], v[62:63], v[14:15] op_sel:[0,1,0]
	v_pk_fma_f32 v[0:1], v[32:33], v[48:49], v[16:17] op_sel_hi:[1,0,1]
	v_pk_fma_f32 v[2:3], v[32:33], v[48:49], v[18:19] op_sel:[0,1,0]
	v_pk_fma_f32 v[4:5], v[32:33], v[50:51], v[20:21] op_sel_hi:[1,0,1]
	v_pk_fma_f32 v[6:7], v[32:33], v[50:51], v[22:23] op_sel:[0,1,0]
	v_pk_fma_f32 v[8:9], v[32:33], v[52:53], v[24:25] op_sel_hi:[1,0,1]
	v_pk_fma_f32 v[10:11], v[32:33], v[52:53], v[26:27] op_sel:[0,1,0]
	v_pk_fma_f32 v[12:13], v[32:33], v[54:55], v[28:29] op_sel_hi:[1,0,1]
	v_pk_fma_f32 v[14:15], v[32:33], v[54:55], v[30:31] op_sel:[0,1,0]
	s_waitcnt lgkmcnt(7)
	v_pk_mul_f32 v[32:33], v[0:1], v[74:75] op_sel_hi:[1,0]
	v_pk_mul_f32 v[36:37], v[0:1], v[64:65] op_sel_hi:[1,0]
	v_pk_fma_f32 v[32:33], v[2:3], v[74:75], v[32:33] op_sel:[0,1,0]
	v_pk_fma_f32 v[36:37], v[2:3], v[64:65], v[36:37] op_sel:[0,1,0]
	v_pk_fma_f32 v[32:33], v[4:5], v[76:77], v[32:33] op_sel_hi:[1,0,1]
	v_pk_fma_f32 v[36:37], v[4:5], v[66:67], v[36:37] op_sel_hi:[1,0,1]
	v_pk_fma_f32 v[32:33], v[6:7], v[76:77], v[32:33] op_sel:[0,1,0]
	v_pk_fma_f32 v[36:37], v[6:7], v[66:67], v[36:37] op_sel:[0,1,0]
	v_pk_fma_f32 v[32:33], v[8:9], v[78:79], v[32:33] op_sel_hi:[1,0,1]
	v_pk_fma_f32 v[36:37], v[8:9], v[68:69], v[36:37] op_sel_hi:[1,0,1]
	v_pk_fma_f32 v[32:33], v[10:11], v[78:79], v[32:33] op_sel:[0,1,0]
	v_pk_fma_f32 v[36:37], v[10:11], v[68:69], v[36:37] op_sel:[0,1,0]
	v_pk_fma_f32 v[32:33], v[12:13], v[80:81], v[32:33] op_sel_hi:[1,0,1]
	v_pk_fma_f32 v[36:37], v[12:13], v[70:71], v[36:37] op_sel_hi:[1,0,1]
	v_pk_fma_f32 v[32:33], v[14:15], v[80:81], v[32:33] op_sel:[0,1,0]
	v_pk_fma_f32 v[36:37], v[14:15], v[70:71], v[36:37] op_sel:[0,1,0]
	ds_write2st64_b32 v134, v36, v37 offset0:12 offset1:13
	ds_read_b128 v[108:111], v132 offset:23280
	ds_read_b128 v[112:115], v132 offset:23296
	s_waitcnt lgkmcnt(3)
	v_add_f32_dpp v32, v32, v32 row_half_mirror row_mask:0xf bank_mask:0xf bound_ctrl:1
	v_add_f32_dpp v33, v33, v33 row_half_mirror row_mask:0xf bank_mask:0xf bound_ctrl:1
	v_pk_fma_f32 v[16:17], v[106:107], v[90:91], v[0:1] op_sel_hi:[1,0,1]
	v_add_f32_dpp v32, v32, v32 quad_perm:[1,0,3,2] row_mask:0xf bank_mask:0xf bound_ctrl:1
	v_add_f32_dpp v33, v33, v33 quad_perm:[1,0,3,2] row_mask:0xf bank_mask:0xf bound_ctrl:1
	v_pk_fma_f32 v[18:19], v[106:107], v[90:91], v[2:3] op_sel:[0,1,0]
	v_add_f32_dpp v32, v32, v32 quad_perm:[2,3,0,1] row_mask:0xf bank_mask:0xf bound_ctrl:1
	v_add_f32_dpp v33, v33, v33 quad_perm:[2,3,0,1] row_mask:0xf bank_mask:0xf bound_ctrl:1
	v_pk_fma_f32 v[20:21], v[106:107], v[92:93], v[4:5] op_sel_hi:[1,0,1]
	v_pk_fma_f32 v[22:23], v[106:107], v[92:93], v[6:7] op_sel:[0,1,0]
	v_pk_fma_f32 v[24:25], v[106:107], v[94:95], v[8:9] op_sel_hi:[1,0,1]
	v_pk_fma_f32 v[26:27], v[106:107], v[94:95], v[10:11] op_sel:[0,1,0]
	v_pk_fma_f32 v[28:29], v[106:107], v[96:97], v[12:13] op_sel_hi:[1,0,1]
	v_pk_fma_f32 v[30:31], v[106:107], v[96:97], v[14:15] op_sel:[0,1,0]
	v_pk_fma_f32 v[0:1], v[32:33], v[82:83], v[16:17] op_sel_hi:[1,0,1]
	v_pk_fma_f32 v[2:3], v[32:33], v[82:83], v[18:19] op_sel:[0,1,0]
	v_pk_fma_f32 v[4:5], v[32:33], v[84:85], v[20:21] op_sel_hi:[1,0,1]
	v_pk_fma_f32 v[6:7], v[32:33], v[84:85], v[22:23] op_sel:[0,1,0]
	v_pk_fma_f32 v[8:9], v[32:33], v[86:87], v[24:25] op_sel_hi:[1,0,1]
	v_pk_fma_f32 v[10:11], v[32:33], v[86:87], v[26:27] op_sel:[0,1,0]
	v_pk_fma_f32 v[12:13], v[32:33], v[88:89], v[28:29] op_sel_hi:[1,0,1]
	v_pk_fma_f32 v[14:15], v[32:33], v[88:89], v[30:31] op_sel:[0,1,0]
	v_pk_mul_f32 v[36:37], v[0:1], v[98:99] op_sel_hi:[1,0]
	v_pk_fma_f32 v[36:37], v[2:3], v[98:99], v[36:37] op_sel:[0,1,0]
	v_pk_fma_f32 v[36:37], v[4:5], v[100:101], v[36:37] op_sel_hi:[1,0,1]
	v_pk_fma_f32 v[36:37], v[6:7], v[100:101], v[36:37] op_sel:[0,1,0]
	v_pk_fma_f32 v[36:37], v[8:9], v[102:103], v[36:37] op_sel_hi:[1,0,1]
	v_pk_fma_f32 v[36:37], v[10:11], v[102:103], v[36:37] op_sel:[0,1,0]
	v_pk_fma_f32 v[36:37], v[12:13], v[104:105], v[36:37] op_sel_hi:[1,0,1]
	v_pk_fma_f32 v[36:37], v[14:15], v[104:105], v[36:37] op_sel:[0,1,0]
	ds_write2st64_b32 v134, v36, v37 offset0:14 offset1:15
	ds_read_b128 v[116:119], v135
	ds_read_b128 v[120:123], v135 offset:16
	ds_read_b128 v[124:127], v135 offset:2048
	ds_read_b128 v[128:131], v135 offset:2064
	s_waitcnt lgkmcnt(4)
	v_pk_mul_f32 v[0:1], v[0:1], v[108:109] op_sel_hi:[1,0]
	v_pk_mul_f32 v[2:3], v[2:3], v[108:109] op_sel:[0,1]
	v_pk_mul_f32 v[4:5], v[4:5], v[110:111] op_sel_hi:[1,0]
	v_pk_mul_f32 v[6:7], v[6:7], v[110:111] op_sel:[0,1]
	v_pk_mul_f32 v[8:9], v[8:9], v[112:113] op_sel_hi:[1,0]
	v_pk_mul_f32 v[10:11], v[10:11], v[112:113] op_sel:[0,1]
	v_pk_mul_f32 v[12:13], v[12:13], v[114:115] op_sel_hi:[1,0]
	v_pk_mul_f32 v[14:15], v[14:15], v[114:115] op_sel:[0,1]
	s_waitcnt lgkmcnt(0)
	v_pk_add_f32 v[116:117], v[116:117], v[118:119]
	v_pk_add_f32 v[120:121], v[120:121], v[122:123]
	v_pk_add_f32 v[124:125], v[124:125], v[126:127]
	v_pk_add_f32 v[128:129], v[128:129], v[130:131]
	v_pk_add_f32 v[116:117], v[116:117], v[120:121]
	v_pk_add_f32 v[124:125], v[124:125], v[128:129]
	v_add_f32_e32 v116, v116, v117
	v_add_f32_e32 v124, v124, v125
	global_atomic_add_f32 v[136:137], v116, off
	global_atomic_add_f32 v[138:139], v124, off
	v_lshl_add_u64 v[136:137], v[136:137], 0, s[38:39]
	v_lshl_add_u64 v[138:139], v[138:139], 0, s[38:39]
	s_xor_b32 s75, s75, 0x6100
	s_waitcnt lgkmcnt(0)
	s_barrier
	s_add_i32 s74, s74, 1
	s_cmp_lt_u32 s74, s73
	s_cbranch_scc1 .Lst_chunk
	s_cmp_eq_u32 s70, 0
	s_cbranch_scc1 .Lst_item_next
	v_mov_b32_e32 v164, v0
	v_mov_b32_e32 v172, v1
	v_mov_b32_e32 v165, v2
	v_mov_b32_e32 v173, v3
	v_mov_b32_e32 v166, v4
	v_mov_b32_e32 v174, v5
	v_mov_b32_e32 v167, v6
	v_mov_b32_e32 v175, v7
	v_mov_b32_e32 v168, v8
	v_mov_b32_e32 v176, v9
	v_mov_b32_e32 v169, v10
	v_mov_b32_e32 v177, v11
	v_mov_b32_e32 v170, v12
	v_mov_b32_e32 v178, v13
	v_mov_b32_e32 v171, v14
	v_mov_b32_e32 v179, v15
	s_add_u32 s4, s20, 0x9000000
	s_addc_u32 s5, s21, 0
	s_add_u32 s4, s4, s40
	s_addc_u32 s5, s5, s41
	v_lshl_add_u64 v[182:183], v[184:185], 0, s[4:5]
	global_store_dwordx4 v[182:183], v[164:167], off
	global_store_dwordx4 v[182:183], v[168:171], off offset:16
	global_store_dwordx4 v[182:183], v[172:175], off offset:256
	global_store_dwordx4 v[182:183], v[176:179], off offset:272
